# u2 plus in-proj epilogue: four serialized gain loads merged into one round trip, RMSNorm row factors loaded in front of the K-loop
# speedup vs baseline: 1.0248x; 1.0014x over previous
; __device__ __forceinline__ void row_rstd8(float (&sc)[2][4], const float* rstd, int row0, int fq) {
;     (void)fq;
; #pragma unroll
;     for (int ai = 0; ai < 2; ++ai)
; #pragma unroll
;         for (int m = 0; m < 4; ++m) sc[ai][m] = rstd[row0 + ai * HALF + m * 16];
; }
; template <class Epi, class Sched, bool ALIGN_EPI = false, bool SP2 = false>
; __device__ __forceinline__ void gemm_phase(PG8_LAS unsigned char* lds, const Gemm g, const Sched& S, const Epi& E, int tid_in) {
;     ...
; #pragma unroll
;         for (int a = 0; a < 2; ++a)
; #pragma unroll
;             for (int b = 0; b < 2; ++b)
; #pragma unroll
;                 for (int m = 0; m < 4; ++m)
; #pragma unroll
;                     for (int n = 0; n < 2; ++n) acc[a][b][m][n] = (f32x4){0.f, 0.f, 0.f, 0.f};
;         cur = nxt; cA = nA; cB = nB; ++ui;
.LBB0_124:
	s_ashr_i32 s63, s62, 31
	s_lshl_b64 s[6:7], s[62:63], 20
	s_add_u32 s64, s12, s6
	s_addc_u32 s65, s14, s7
	s_and_b64 s[6:7], s[4:5], exec
	s_cselect_b32 s63, s65, s75
	s_cselect_b32 s71, s64, s74
	s_ashr_i32 s61, s60, 31
	s_lshl_b64 s[6:7], s[60:61], 20
	s_add_u32 s66, s50, s6
	s_addc_u32 s67, s51, s7
	s_and_b64 s[6:7], s[4:5], exec
	s_cselect_b32 s61, s67, s73
	s_cselect_b32 s85, s66, s72
	s_add_u32 s6, s74, 0x80080
	s_addc_u32 s7, s75, 0
	s_add_u32 s87, s72, 0x100
	v_mov_b32_e32 v0, 0
	s_addc_u32 s90, s73, 0
	s_mov_b32 s95, -2
	v_mov_b32_e32 v1, v0
	v_mov_b32_e32 v2, v0
	v_mov_b32_e32 v3, v0
	v_mov_b32_e32 v4, v0
	v_mov_b32_e32 v5, v0
	v_mov_b32_e32 v6, v0
	v_mov_b32_e32 v7, v0
	s_waitcnt vmcnt(0)
	v_mov_b32_e32 v16, v0
	v_mov_b32_e32 v17, v0
	v_mov_b32_e32 v18, v0
	v_mov_b32_e32 v19, v0
	v_mov_b32_e32 v22, v0
	v_mov_b32_e32 v23, v0
	v_mov_b32_e32 v24, v0
	v_mov_b32_e32 v25, v0
	v_mov_b32_e32 v34, v0
	v_mov_b32_e32 v35, v0
	v_mov_b32_e32 v36, v0
	v_mov_b32_e32 v37, v0
	v_mov_b32_e32 v38, v0
	v_mov_b32_e32 v39, v0
	v_mov_b32_e32 v40, v0
	v_mov_b32_e32 v41, v0
	v_mov_b32_e32 v50, v0
	v_mov_b32_e32 v51, v0
	v_mov_b32_e32 v52, v0
	v_mov_b32_e32 v53, v0
	v_mov_b32_e32 v54, v0
	v_mov_b32_e32 v55, v0
	v_mov_b32_e32 v56, v0
	v_mov_b32_e32 v57, v0
	v_mov_b32_e32 v8, v0
	v_mov_b32_e32 v9, v0
	v_mov_b32_e32 v10, v0
	v_mov_b32_e32 v11, v0
	v_mov_b32_e32 v12, v0
	v_mov_b32_e32 v13, v0
	v_mov_b32_e32 v14, v0
	v_mov_b32_e32 v15, v0
	v_mov_b32_e32 v26, v0
	v_mov_b32_e32 v27, v0
	v_mov_b32_e32 v28, v0
	v_mov_b32_e32 v29, v0
	v_mov_b32_e32 v30, v0
	v_mov_b32_e32 v31, v0
	v_mov_b32_e32 v32, v0
	v_mov_b32_e32 v33, v0
	v_mov_b32_e32 v42, v0
	v_mov_b32_e32 v43, v0
	v_mov_b32_e32 v44, v0
	v_mov_b32_e32 v45, v0
	v_mov_b32_e32 v46, v0
	v_mov_b32_e32 v47, v0
	v_mov_b32_e32 v48, v0
	v_mov_b32_e32 v49, v0
	v_mov_b32_e32 v58, v0
	v_mov_b32_e32 v59, v0
	v_mov_b32_e32 v60, v0
	v_mov_b32_e32 v61, v0
	v_mov_b32_e32 v62, v0
	v_mov_b32_e32 v63, v0
	v_mov_b32_e32 v64, v0
	v_mov_b32_e32 v65, v0
	v_mov_b32_e32 v66, v0
	v_mov_b32_e32 v67, v0
	v_mov_b32_e32 v68, v0
	v_mov_b32_e32 v69, v0
	v_mov_b32_e32 v70, v0
	v_mov_b32_e32 v71, v0
	v_mov_b32_e32 v72, v0
	v_mov_b32_e32 v73, v0
	v_mov_b32_e32 v82, v0
	v_mov_b32_e32 v83, v0
	v_mov_b32_e32 v84, v0
	v_mov_b32_e32 v85, v0
	v_mov_b32_e32 v86, v0
	v_mov_b32_e32 v87, v0
	v_mov_b32_e32 v88, v0
	v_mov_b32_e32 v89, v0
	v_mov_b32_e32 v98, v0
	v_mov_b32_e32 v99, v0
	v_mov_b32_e32 v100, v0
	v_mov_b32_e32 v101, v0
	v_mov_b32_e32 v102, v0
	v_mov_b32_e32 v103, v0
	v_mov_b32_e32 v104, v0
	v_mov_b32_e32 v105, v0
	v_mov_b32_e32 v114, v0
	v_mov_b32_e32 v115, v0
	v_mov_b32_e32 v116, v0
	v_mov_b32_e32 v117, v0
	v_mov_b32_e32 v118, v0
	v_mov_b32_e32 v119, v0
	v_mov_b32_e32 v120, v0
	v_mov_b32_e32 v121, v0
	v_mov_b32_e32 v74, v0
	v_mov_b32_e32 v75, v0
	v_mov_b32_e32 v76, v0
	v_mov_b32_e32 v77, v0
	v_mov_b32_e32 v78, v0
	v_mov_b32_e32 v79, v0
	v_mov_b32_e32 v80, v0
	v_mov_b32_e32 v81, v0
	v_mov_b32_e32 v90, v0
	v_mov_b32_e32 v91, v0
	v_mov_b32_e32 v92, v0
	v_mov_b32_e32 v93, v0
	v_mov_b32_e32 v94, v0
	v_mov_b32_e32 v95, v0
	v_mov_b32_e32 v96, v0
	v_mov_b32_e32 v97, v0
	v_mov_b32_e32 v106, v0
	v_mov_b32_e32 v107, v0
	v_mov_b32_e32 v108, v0
	v_mov_b32_e32 v109, v0
	v_mov_b32_e32 v110, v0
	v_mov_b32_e32 v111, v0
	v_mov_b32_e32 v112, v0
	v_mov_b32_e32 v113, v0
	v_mov_b32_e32 v122, v0
	v_mov_b32_e32 v123, v0
	v_mov_b32_e32 v124, v0
	v_mov_b32_e32 v125, v0
	v_mov_b32_e32 v126, v0
	v_mov_b32_e32 v127, v0
	v_mov_b32_e32 v128, v0
	v_mov_b32_e32 v129, v0
	v_and_b32_e32 v234, 15, v250
	s_lshl_b32 s98, s68, 8
	s_add_i32 s98, s98, s43
	v_or_b32_e32 v234, s98, v234
	v_ashrrev_i32_e32 v235, 31, v234
	v_lshl_add_u64 v[234:235], v[234:235], 2, s[56:57]
	global_load_dword v236, v[234:235], off
	global_load_dword v237, v[234:235], off offset:64
	global_load_dword v238, v[234:235], off offset:128
	global_load_dword v239, v[234:235], off offset:192
	global_load_dword v240, v[234:235], off offset:512
	global_load_dword v241, v[234:235], off offset:576
	global_load_dword v242, v[234:235], off offset:640
	global_load_dword v243, v[234:235], off offset:704

;     __device__ __forceinline__ void operator()(const f32x4 (&acc)[2][2][4][2], const Unit& u, int wr, int wc, int fr_, int fq_) const {
;         unsigned lz_ = 0u; asm volatile("" : "+v"(lz_)); const int ln_ = __builtin_amdgcn_mbcnt_hi(~0u, __builtin_amdgcn_mbcnt_lo(~0u, lz_)); const int fr = ln_ & 15, fq = ln_ >> 4; (void)fr_; (void)fq_;
;         const int row0 = u.pm * BM + wr * 64 + fr; const int slot = 4 * u.pn + wc;
;         const float* gp = nullptr; float gsc = 1.0f;
;         if (slot < 8) { gp = aq; gsc = 0.125f * 1.4426950408889634f; } else if (slot < 10) gp = ak; else if (slot >= 36 && slot < 52) { gp = cq; gsc = 0.125f * 1.4426950408889634f; } else if (slot >= 52 && slot < 68) gp = ck;
;         f32x4 gv[2][2];
; #pragma unroll
;         for (int bj = 0; bj < 2; ++bj)
; #pragma unroll
;             for (int n = 0; n < 2; ++n) gv[bj][n] = gp ? *(const f32x4*)(gp + 32 * bj + 8 * fq + 4 * n) * gsc : (f32x4){1.f, 1.f, 1.f, 1.f};
;         float scs[2][4]; row_rstd8(scs, rs, row0, fq);
; #pragma unroll
;         for (int ai = 0; ai < 2; ++ai)
; #pragma unroll
;             for (int m = 0; m < 4; ++m) { const int row = row0 + ai * HALF + m * 16; const float sc = scs[ai][m];
;                 f32x4 v[2][2];
; #pragma unroll
;                 for (int bj = 0; bj < 2; ++bj)
; #pragma unroll
;                     for (int n = 0; n < 2; ++n) v[bj][n] = acc[ai][bj][m][n] * sc;
;                 if (gp) { float ss = 0.f;
; #pragma unroll
;                     for (int bj = 0; bj < 2; ++bj)
; #pragma unroll
;                         for (int n = 0; n < 2; ++n) ss += (v[bj][n][0] * v[bj][n][0] + v[bj][n][1] * v[bj][n][1]) + (v[bj][n][2] * v[bj][n][2] + v[bj][n][3] * v[bj][n][3]);
;                     ss = sum_fq(ss);
;                     const float f = __builtin_amdgcn_rsqf(ss * (1.0f / 64.0f) + 1e-6f);
; #pragma unroll
;                     for (int bj = 0; bj < 2; ++bj)
; #pragma unroll
;                         for (int n = 0; n < 2; ++n) v[bj][n] = v[bj][n] * (gv[bj][n] * f); }
.LBB0_131:
	v_mbcnt_lo_u32_b32 v142, -1, v142
	v_mbcnt_hi_u32_b32 v164, -1, v142
	v_ashrrev_i32_e32 v142, 1, v164
	v_and_b32_e32 v162, -8, v142
	s_cmp_lg_u64 s[6:7], 0
	v_ashrrev_i32_e32 v163, 31, v162
	s_cselect_b64 s[72:73], -1, 0
	s_cmp_eq_u64 s[6:7], 0
	v_mov_b32_e32 v159, v158
	v_lshl_add_u64 v[160:161], v[162:163], 2, s[6:7]
	v_mov_b32_e32 v142, 1.0
	v_mov_b32_e32 v146, 1.0
	v_mov_b32_e32 v147, 1.0
	v_mov_b32_e32 v144, 1.0
	v_mov_b32_e32 v145, 1.0
	s_cbranch_scc1 .LBB0_133
	global_load_dwordx4 v[146:149], v[160:161], off
	global_load_dwordx4 v[150:153], v[160:161], off offset:16
	global_load_dwordx4 v[184:187], v[160:161], off offset:128
	global_load_dwordx4 v[170:173], v[160:161], off offset:144
	v_mov_b32_e32 v144, v158
	v_mov_b32_e32 v145, v158
	s_waitcnt vmcnt(0)
	v_pk_mul_f32 v[144:145], v[144:145], v[148:149]
	v_pk_mul_f32 v[146:147], v[158:159], v[146:147]
.LBB0_133:
	v_cndmask_b32_e64 v143, 0, 1, s[72:73]
	v_cmp_ne_u32_e64 s[6:7], 1, v143
	s_andn2_b64 vcc, exec, s[72:73]
	v_mov_b32_e32 v143, 1.0
	v_mov_b32_e32 v148, 1.0
	v_mov_b32_e32 v149, 1.0
	s_cbranch_vccnz .LBB0_135
	v_mov_b32_e32 v142, v158
	v_mov_b32_e32 v143, v158
	v_pk_mul_f32 v[148:149], v[142:143], v[152:153]
	v_pk_mul_f32 v[142:143], v[158:159], v[150:151]
.LBB0_135:
	v_mov_b32_e32 v150, 1.0
	s_and_b64 vcc, exec, s[6:7]
	v_mov_b32_e32 v154, 1.0
	v_mov_b32_e32 v155, 1.0
	v_mov_b32_e32 v152, 1.0
	v_mov_b32_e32 v153, 1.0
	s_cbranch_vccnz .LBB0_137
	v_mov_b32_e32 v152, v158
	v_mov_b32_e32 v153, v158
	v_pk_mul_f32 v[152:153], v[152:153], v[186:187]
	v_pk_mul_f32 v[154:155], v[158:159], v[184:185]
.LBB0_137:
	s_and_b64 vcc, exec, s[6:7]
	v_mov_b32_e32 v151, 1.0
	v_mov_b32_e32 v156, 1.0
	v_mov_b32_e32 v157, 1.0
	s_cbranch_vccnz .LBB0_139
	v_mov_b32_e32 v150, v158
	v_mov_b32_e32 v151, v158
	v_pk_mul_f32 v[156:157], v[150:151], v[172:173]
	v_pk_mul_f32 v[150:151], v[158:159], v[170:171]
.LBB0_139:
	s_lshl_b32 s61, s68, 8
	s_add_i32 s61, s61, s43
	v_and_or_b32 v166, v164, 15, s61
	v_ashrrev_i32_e32 v167, 31, v166
	v_lshl_add_u64 v[158:159], v[166:167], 2, s[56:57]
	v_mov_b32_e32 v178, v236
	v_mov_b32_e32 v174, v237
	v_mov_b32_e32 v172, v238
	v_mov_b32_e32 v170, v239
	v_mov_b32_e32 v168, v240
	v_mov_b32_e32 v164, v241
	v_mov_b32_e32 v160, v242
	v_mov_b32_e32 v158, v243
	s_and_b64 vcc, exec, s[6:7]
	v_pk_mul_f32 v[128:129], v[128:129], v[178:179] op_sel_hi:[1,0]
	v_pk_mul_f32 v[176:177], v[126:127], v[178:179] op_sel_hi:[1,0]
	v_pk_mul_f32 v[124:125], v[124:125], v[178:179] op_sel_hi:[1,0]
	v_pk_mul_f32 v[126:127], v[122:123], v[178:179] op_sel_hi:[1,0]
	v_pk_mul_f32 v[120:121], v[120:121], v[178:179] op_sel_hi:[1,0]
	v_pk_mul_f32 v[122:123], v[118:119], v[178:179] op_sel_hi:[1,0]
	v_pk_mul_f32 v[116:117], v[116:117], v[178:179] op_sel_hi:[1,0]
	v_pk_mul_f32 v[118:119], v[114:115], v[178:179] op_sel_hi:[1,0]
	s_cbranch_vccnz .LBB0_141
	v_mul_f32_e32 v114, v177, v177
	v_mul_f32_e32 v115, v129, v129
	v_fmac_f32_e32 v114, v176, v176
	v_fmac_f32_e32 v115, v128, v128
	v_add_f32_e32 v114, v114, v115
	v_mul_f32_e32 v115, v127, v127
	v_mul_f32_e32 v159, v125, v125
	v_fmac_f32_e32 v115, v126, v126
	v_fmac_f32_e32 v159, v124, v124
	v_add_f32_e32 v115, v115, v159
	v_add_f32_e32 v114, v114, v115
	v_mul_f32_e32 v115, v123, v123
	v_mul_f32_e32 v159, v121, v121
	v_fmac_f32_e32 v115, v122, v122
	v_fmac_f32_e32 v159, v120, v120
	v_add_f32_e32 v115, v115, v159
	v_add_f32_e32 v114, v115, v114
	v_mul_f32_e32 v115, v119, v119
	v_mul_f32_e32 v159, v117, v117
	v_fmac_f32_e32 v115, v118, v118
	v_fmac_f32_e32 v159, v116, v116
	v_add_f32_e32 v115, v115, v159
	v_add_f32_e32 v114, v115, v114
	v_mov_b32_e32 v115, v114
	s_nop 1
	v_permlane16_swap_b32_e32 v114, v115
	v_add_f32_e32 v114, v114, v115
	v_mov_b32_e32 v115, v114
	s_nop 1
	v_permlane32_swap_b32_e32 v114, v115
	v_add_f32_e32 v114, v114, v115
	v_fmamk_f32 v114, v114, 0x3c800000, v244
	v_rsq_f32_e32 v114, v114
	s_nop 0
	v_pk_mul_f32 v[178:179], v[146:147], v[114:115] op_sel_hi:[1,0]
	v_pk_mul_f32 v[180:181], v[144:145], v[114:115] op_sel_hi:[1,0]
	v_pk_mul_f32 v[176:177], v[176:177], v[178:179]
	v_pk_mul_f32 v[178:179], v[142:143], v[114:115] op_sel_hi:[1,0]
	v_pk_mul_f32 v[128:129], v[128:129], v[180:181]
	v_pk_mul_f32 v[180:181], v[148:149], v[114:115] op_sel_hi:[1,0]
	v_pk_mul_f32 v[126:127], v[126:127], v[178:179]
	v_pk_mul_f32 v[178:179], v[154:155], v[114:115] op_sel_hi:[1,0]
	v_pk_mul_f32 v[124:125], v[124:125], v[180:181]
	v_pk_mul_f32 v[180:181], v[152:153], v[114:115] op_sel_hi:[1,0]
	v_pk_mul_f32 v[122:123], v[122:123], v[178:179]
	v_pk_mul_f32 v[178:179], v[150:151], v[114:115] op_sel_hi:[1,0]
	v_pk_mul_f32 v[114:115], v[156:157], v[114:115] op_sel_hi:[1,0]
	v_pk_mul_f32 v[120:121], v[120:121], v[180:181]
	v_pk_mul_f32 v[116:117], v[116:117], v[114:115]
	v_pk_mul_f32 v[118:119], v[118:119], v[178:179]
